# v42 plus: the last four LDS-DMA loads per iteration of the w_in / up K-loops also use the SADDR form (all 80 staging loads now without a VALU address add)
# speedup vs baseline: 1.0076x; 1.0014x over previous
; #define PG8_STAGE(bufoff, gbase, voff) do { _Pragma("unroll") for (int _i = 0; _i < 2; ++_i) \
;         __builtin_amdgcn_global_load_lds((const unsigned*)((const char*)(gbase) + (voff)[_i]), (PG8_LAS unsigned*)(lds + (bufoff) + ldsw + _i * 8192), 16, 0, 0); } while (0)
; #define PG8_LDA(dst, b, h) do { _Pragma("unroll") for (int m = 0; m < 4; ++m) _Pragma("unroll") for (int k = 0; k < 2; ++k) dst[m][k] = *(const PG8_LAS bf16x8*)(lds + PG8_SA(b, h) + aoff + m * 2048 + k * 1024); } while (0)
; #define PG8_LDB(dst, b, h) do { _Pragma("unroll") for (int n = 0; n < 2; ++n) _Pragma("unroll") for (int k = 0; k < 2; ++k) dst[n][k] = *(const PG8_LAS bf16x8*)(lds + PG8_SB(b, h) + boff + n * 2048 + k * 1024); } while (0)
; #define PG8_MMA(ai, bj, At, Bt) do { __builtin_amdgcn_s_setprio(1); _Pragma("unroll") for (int m = 0; m < 4; ++m) _Pragma("unroll") for (int n = 0; n < 2; ++n) _Pragma("unroll") for (int k = 0; k < 2; ++k) \
;         acc[ai][bj][m][n] = __builtin_amdgcn_mfma_f32_16x16x32_bf16(Bt[n][k], At[m][k], acc[ai][bj][m][n], 0, 0, 0); __builtin_amdgcn_s_setprio(0); } while (0)
; #define PG8_WAIT_V(n) asm volatile("s_waitcnt vmcnt(" #n ")" ::: "memory")
; #define PG8_WAIT_L(n) asm volatile("s_waitcnt lgkmcnt(" #n ")" ::: "memory")
; template <class Epi, class Sched, bool ALIGN_EPI = false, bool SP2 = false>
; __device__ __forceinline__ void gemm_phase(PG8_LAS unsigned char* lds, const Gemm g, const Sched& S, const Epi& E) {
;     ...
;             const bool last = (t == nt - 2);
;             const char* a1 = cA + (size_t)(t + 1) * kstep;
;             const char* a2 = last ? nA : cA + (size_t)(t + 2) * kstep; const char* b2 = last ? nB : cB + (size_t)(t + 2) * kstep;
;             const char* a3 = a2 + kstep; const char* b3 = b2 + kstep;
;             if (last && has_next) S.a_ready(nxt);
;             if constexpr (SP2) {
;             PG8_LDB(B0, 0, 0); PG8_LDB(B1, 0, 1); PG8_SCHED; PG8_LDA(At, 0, 0); PG8_STAGE(PG8_SA(1, 1), a1 + hstep, voffA);
;             PG8_WAIT_V(8); PG8_WAIT_L(0); PG8_BAR; PG8_MMA(0, 0, At, B0); PG8_MMA(0, 1, At, B1); PG8_BAR; PG8_SCHED;
;             PG8_LDA(At, 0, 1); PG8_STAGE(PG8_SB(0, 0), b2, voffB); PG8_STAGE(PG8_SB(0, 1), b2 + hstepB, voffB); PG8_STAGE(PG8_SA(0, 0), a2, voffA);
;             PG8_WAIT_V(8); PG8_WAIT_L(0); PG8_BAR; PG8_MMA(1, 0, At, B0); PG8_MMA(1, 1, At, B1); PG8_BAR; PG8_SCHED;
.LBB0_170:
	s_add_u32 s9, s70, s46
	s_addc_u32 s10, s71, s47
	s_add_u32 s9, s9, 0x100
	s_addc_u32 s10, s10, 0
	s_add_u32 s100, s9, 0x7ff80
	s_addc_u32 s101, s10, 0
	s_add_u32 s11, s93, s46
	s_addc_u32 s12, s94, s47
	s_add_i32 s13, 0, 0x10000
	s_cmpk_eq_i32 s46, 0xf00
	s_cselect_b32 s85, s4, s10
	s_cselect_b32 s84, s5, s9
	s_cselect_b32 s81, s6, s12
	s_cselect_b32 s80, s7, s11
	s_add_i32 s9, 0, 0x14000
	v_add_u32_e32 v160, s13, v139
	v_add_u32_e32 v178, s9, v139
	ds_read_b128 v[148:151], v160
	ds_read_b128 v[152:155], v160 offset:1024
	ds_read_b128 v[156:159], v160 offset:2048
	ds_read_b128 v[160:163], v160 offset:3072
	ds_read_b128 v[166:169], v178
	ds_read_b128 v[170:173], v178 offset:1024
	ds_read_b128 v[174:177], v178 offset:2048
	ds_read_b128 v[178:181], v178 offset:3072
	s_add_i32 m0, s1, 0xc000
	ds_read_b128 v[182:185], v165
	ds_read_b128 v[206:209], v165 offset:1024
	ds_read_b128 v[210:213], v165 offset:2048
	ds_read_b128 v[214:217], v165 offset:3072
	ds_read_b128 v[218:221], v165 offset:4096
	ds_read_b128 v[236:239], v165 offset:5120
	ds_read_b128 v[240:243], v165 offset:6144
	ds_read_b128 v[244:247], v165 offset:7168
	global_load_lds_dwordx4 v140, s[100:101]
	s_add_i32 m0, s1, 0xe000
	s_nop 0
	global_load_lds_dwordx4 v142, s[100:101]
	s_waitcnt vmcnt(8)
	s_waitcnt lgkmcnt(0)
	s_barrier
	v_mfma_f32_16x16x32_bf16 v[126:129], v[148:151], v[182:185], v[126:129]
	v_mfma_f32_16x16x32_bf16 v[122:125], v[156:159], v[182:185], v[122:125]
	v_mfma_f32_16x16x32_bf16 v[118:121], v[148:151], v[210:213], v[118:121]
	v_mfma_f32_16x16x32_bf16 v[114:117], v[156:159], v[210:213], v[114:117]
	v_mfma_f32_16x16x32_bf16 v[110:113], v[148:151], v[218:221], v[110:113]
	v_mfma_f32_16x16x32_bf16 v[106:109], v[156:159], v[218:221], v[106:109]
	v_mfma_f32_16x16x32_bf16 v[102:105], v[148:151], v[240:243], v[102:105]
	v_mfma_f32_16x16x32_bf16 v[98:101], v[156:159], v[240:243], v[98:101]
	v_mfma_f32_16x16x32_bf16 v[126:129], v[152:155], v[206:209], v[126:129]
	v_mfma_f32_16x16x32_bf16 v[122:125], v[160:163], v[206:209], v[122:125]
	v_mfma_f32_16x16x32_bf16 v[118:121], v[152:155], v[214:217], v[118:121]
	v_mfma_f32_16x16x32_bf16 v[114:117], v[160:163], v[214:217], v[114:117]
	v_mfma_f32_16x16x32_bf16 v[110:113], v[152:155], v[236:239], v[110:113]
	v_mfma_f32_16x16x32_bf16 v[106:109], v[160:163], v[236:239], v[106:109]
	v_mfma_f32_16x16x32_bf16 v[102:105], v[152:155], v[244:247], v[102:105]
	v_mfma_f32_16x16x32_bf16 v[98:101], v[160:163], v[244:247], v[98:101]
	v_mfma_f32_16x16x32_bf16 v[94:97], v[166:169], v[182:185], v[94:97]
	v_mfma_f32_16x16x32_bf16 v[90:93], v[174:177], v[182:185], v[90:93]
	v_mfma_f32_16x16x32_bf16 v[86:89], v[166:169], v[210:213], v[86:89]
	v_mfma_f32_16x16x32_bf16 v[82:85], v[174:177], v[210:213], v[82:85]
	v_mfma_f32_16x16x32_bf16 v[78:81], v[166:169], v[218:221], v[78:81]
	v_mfma_f32_16x16x32_bf16 v[74:77], v[174:177], v[218:221], v[74:77]
	v_mfma_f32_16x16x32_bf16 v[70:73], v[166:169], v[240:243], v[70:73]
	v_mfma_f32_16x16x32_bf16 v[66:69], v[174:177], v[240:243], v[66:69]
	v_mfma_f32_16x16x32_bf16 v[94:97], v[170:173], v[206:209], v[94:97]
	v_mfma_f32_16x16x32_bf16 v[90:93], v[178:181], v[206:209], v[90:93]
	v_mfma_f32_16x16x32_bf16 v[86:89], v[170:173], v[214:217], v[86:89]
	v_mfma_f32_16x16x32_bf16 v[82:85], v[178:181], v[214:217], v[82:85]
	v_mfma_f32_16x16x32_bf16 v[78:81], v[170:173], v[236:239], v[78:81]
	v_mfma_f32_16x16x32_bf16 v[74:77], v[178:181], v[236:239], v[74:77]
	v_mfma_f32_16x16x32_bf16 v[70:73], v[170:173], v[244:247], v[70:73]
	v_mfma_f32_16x16x32_bf16 v[66:69], v[178:181], v[244:247], v[66:69]
	s_barrier
	s_add_i32 s10, s13, s0
	s_mov_b32 m0, s10
	ds_read_b128 v[182:185], v165 offset:16384
	ds_read_b128 v[206:209], v165 offset:17408
	ds_read_b128 v[210:213], v165 offset:18432
	ds_read_b128 v[214:217], v165 offset:19456
	ds_read_b128 v[218:221], v165 offset:20480
	ds_read_b128 v[236:239], v165 offset:21504
	ds_read_b128 v[240:243], v165 offset:22528
	ds_read_b128 v[244:247], v165 offset:23552
	global_load_lds_dwordx4 v132, s[80:81]
	s_add_i32 m0, s10, 0x2000
	s_add_u32 s10, s80, 0x20000
	s_addc_u32 s11, s81, 0
	s_add_i32 s9, s9, s0
	global_load_lds_dwordx4 v136, s[80:81]
	s_mov_b32 m0, s9
	s_nop 0
	global_load_lds_dwordx4 v132, s[10:11]
	s_add_i32 m0, s9, 0x2000
	s_nop 0
	global_load_lds_dwordx4 v136, s[10:11]
	s_mov_b32 m0, s1
	s_nop 0
	global_load_lds_dwordx4 v130, s[84:85]
	s_mov_b32 m0, s25
	s_nop 0
	global_load_lds_dwordx4 v134, s[84:85]
	s_waitcnt vmcnt(8)
	s_waitcnt lgkmcnt(0)
	s_barrier
	v_mfma_f32_16x16x32_bf16 v[62:65], v[148:151], v[182:185], v[62:65]
	v_mfma_f32_16x16x32_bf16 v[58:61], v[156:159], v[182:185], v[58:61]
	v_mfma_f32_16x16x32_bf16 v[54:57], v[148:151], v[210:213], v[54:57]
	v_mfma_f32_16x16x32_bf16 v[50:53], v[156:159], v[210:213], v[50:53]
	v_mfma_f32_16x16x32_bf16 v[46:49], v[148:151], v[218:221], v[46:49]
	v_mfma_f32_16x16x32_bf16 v[42:45], v[156:159], v[218:221], v[42:45]
	v_mfma_f32_16x16x32_bf16 v[38:41], v[148:151], v[240:243], v[38:41]
	v_mfma_f32_16x16x32_bf16 v[34:37], v[156:159], v[240:243], v[34:37]
	v_mfma_f32_16x16x32_bf16 v[62:65], v[152:155], v[206:209], v[62:65]
	v_mfma_f32_16x16x32_bf16 v[58:61], v[160:163], v[206:209], v[58:61]
	v_mfma_f32_16x16x32_bf16 v[54:57], v[152:155], v[214:217], v[54:57]
	v_mfma_f32_16x16x32_bf16 v[50:53], v[160:163], v[214:217], v[50:53]
	v_mfma_f32_16x16x32_bf16 v[46:49], v[152:155], v[236:239], v[46:49]
	v_mfma_f32_16x16x32_bf16 v[42:45], v[160:163], v[236:239], v[42:45]
	v_mfma_f32_16x16x32_bf16 v[38:41], v[152:155], v[244:247], v[38:41]
	v_mfma_f32_16x16x32_bf16 v[34:37], v[160:163], v[244:247], v[34:37]
	v_mfma_f32_16x16x32_bf16 v[30:33], v[166:169], v[182:185], v[30:33]
	v_mfma_f32_16x16x32_bf16 v[26:29], v[174:177], v[182:185], v[26:29]
	v_mfma_f32_16x16x32_bf16 v[22:25], v[166:169], v[210:213], v[22:25]
	v_mfma_f32_16x16x32_bf16 v[18:21], v[174:177], v[210:213], v[18:21]
	v_mfma_f32_16x16x32_bf16 v[14:17], v[166:169], v[218:221], v[14:17]
	v_mfma_f32_16x16x32_bf16 v[10:13], v[174:177], v[218:221], v[10:13]
	v_mfma_f32_16x16x32_bf16 v[6:9], v[166:169], v[240:243], v[6:9]
	v_mfma_f32_16x16x32_bf16 v[2:5], v[174:177], v[240:243], v[2:5]
	v_mfma_f32_16x16x32_bf16 v[30:33], v[170:173], v[206:209], v[30:33]
	v_mfma_f32_16x16x32_bf16 v[26:29], v[178:181], v[206:209], v[26:29]
	v_mfma_f32_16x16x32_bf16 v[22:25], v[170:173], v[214:217], v[22:25]
	v_mfma_f32_16x16x32_bf16 v[18:21], v[178:181], v[214:217], v[18:21]
	v_mfma_f32_16x16x32_bf16 v[14:17], v[170:173], v[236:239], v[14:17]
	v_mfma_f32_16x16x32_bf16 v[10:13], v[178:181], v[236:239], v[10:13]
	v_mfma_f32_16x16x32_bf16 v[6:9], v[170:173], v[244:247], v[6:9]
	v_mfma_f32_16x16x32_bf16 v[2:5], v[178:181], v[244:247], v[2:5]
	s_barrier
; #define PG8_STAGE(bufoff, gbase, voff) do { _Pragma("unroll") for (int _i = 0; _i < 2; ++_i) \
;         __builtin_amdgcn_global_load_lds((const unsigned*)((const char*)(gbase) + (voff)[_i]), (PG8_LAS unsigned*)(lds + (bufoff) + ldsw + _i * 8192), 16, 0, 0); } while (0)
; #define PG8_LDA(dst, b, h) do { _Pragma("unroll") for (int m = 0; m < 4; ++m) _Pragma("unroll") for (int k = 0; k < 2; ++k) dst[m][k] = *(const PG8_LAS bf16x8*)(lds + PG8_SA(b, h) + aoff + m * 2048 + k * 1024); } while (0)
; #define PG8_LDB(dst, b, h) do { _Pragma("unroll") for (int n = 0; n < 2; ++n) _Pragma("unroll") for (int k = 0; k < 2; ++k) dst[n][k] = *(const PG8_LAS bf16x8*)(lds + PG8_SB(b, h) + boff + n * 2048 + k * 1024); } while (0)
; #define PG8_MMA(ai, bj, At, Bt) do { __builtin_amdgcn_s_setprio(1); _Pragma("unroll") for (int m = 0; m < 4; ++m) _Pragma("unroll") for (int n = 0; n < 2; ++n) _Pragma("unroll") for (int k = 0; k < 2; ++k) \
;         acc[ai][bj][m][n] = __builtin_amdgcn_mfma_f32_16x16x32_bf16(Bt[n][k], At[m][k], acc[ai][bj][m][n], 0, 0, 0); __builtin_amdgcn_s_setprio(0); } while (0)
; #define PG8_WAIT_V(n) asm volatile("s_waitcnt vmcnt(" #n ")" ::: "memory")
; #define PG8_WAIT_L(n) asm volatile("s_waitcnt lgkmcnt(" #n ")" ::: "memory")
; #define PG8_BAR __builtin_amdgcn_s_barrier()
; #define PG8_SCHED __builtin_amdgcn_sched_barrier(0)
; template <class Epi, class Sched, bool ALIGN_EPI = false, bool SP2 = false>
; __device__ __forceinline__ void gemm_phase(PG8_LAS unsigned char* lds, const Gemm g, const Sched& S, const Epi& E) {
;     ...
;             PG8_LDB(B0, 1, 0); PG8_LDB(B1, 1, 1); PG8_SCHED; PG8_LDA(At, 1, 0); PG8_STAGE(PG8_SA(0, 1), a2 + hstep, voffA);
;             PG8_WAIT_V(8); PG8_WAIT_L(0); PG8_BAR; PG8_MMA(0, 0, At, B0); PG8_MMA(0, 1, At, B1); PG8_BAR; PG8_SCHED;
;             PG8_LDA(At, 1, 1); PG8_STAGE(PG8_SB(1, 0), b3, voffB); PG8_STAGE(PG8_SB(1, 1), b3 + hstepB, voffB); PG8_STAGE(PG8_SA(1, 0), a3, voffA);
;             PG8_WAIT_V(8); PG8_WAIT_L(0); PG8_BAR; PG8_MMA(1, 0, At, B0); PG8_MMA(1, 1, At, B1); PG8_BAR; PG8_SCHED;
	s_add_i32 s9, 0, 0x18000
	s_add_i32 s12, 0, 0x1c000
	v_add_u32_e32 v160, s9, v139
	v_add_u32_e32 v178, s12, v139
	ds_read_b128 v[148:151], v160
	ds_read_b128 v[152:155], v160 offset:1024
	ds_read_b128 v[156:159], v160 offset:2048
	ds_read_b128 v[160:163], v160 offset:3072
	ds_read_b128 v[166:169], v178
	ds_read_b128 v[170:173], v178 offset:1024
	ds_read_b128 v[174:177], v178 offset:2048
	ds_read_b128 v[178:181], v178 offset:3072
	s_add_u32 s10, s84, 0x80000
	s_addc_u32 s11, s85, 0
	s_mov_b32 m0, s42
	ds_read_b128 v[182:185], v165 offset:32768
	ds_read_b128 v[206:209], v165 offset:33792
	ds_read_b128 v[210:213], v165 offset:34816
	ds_read_b128 v[214:217], v165 offset:35840
	ds_read_b128 v[218:221], v165 offset:36864
	ds_read_b128 v[236:239], v165 offset:37888
	ds_read_b128 v[240:243], v165 offset:38912
	ds_read_b128 v[244:247], v165 offset:39936
	global_load_lds_dwordx4 v130, s[10:11]
	s_mov_b32 m0, s51
	s_nop 0
	global_load_lds_dwordx4 v134, s[10:11]
	s_waitcnt vmcnt(8)
	s_waitcnt lgkmcnt(0)
	s_barrier
	v_mfma_f32_16x16x32_bf16 v[126:129], v[148:151], v[182:185], v[126:129]
	v_mfma_f32_16x16x32_bf16 v[122:125], v[156:159], v[182:185], v[122:125]
	v_mfma_f32_16x16x32_bf16 v[118:121], v[148:151], v[210:213], v[118:121]
	v_mfma_f32_16x16x32_bf16 v[114:117], v[156:159], v[210:213], v[114:117]
	v_mfma_f32_16x16x32_bf16 v[110:113], v[148:151], v[218:221], v[110:113]
	v_mfma_f32_16x16x32_bf16 v[106:109], v[156:159], v[218:221], v[106:109]
	v_mfma_f32_16x16x32_bf16 v[102:105], v[148:151], v[240:243], v[102:105]
	v_mfma_f32_16x16x32_bf16 v[98:101], v[156:159], v[240:243], v[98:101]
	v_mfma_f32_16x16x32_bf16 v[126:129], v[152:155], v[206:209], v[126:129]
	v_mfma_f32_16x16x32_bf16 v[122:125], v[160:163], v[206:209], v[122:125]
	v_mfma_f32_16x16x32_bf16 v[118:121], v[152:155], v[214:217], v[118:121]
	v_mfma_f32_16x16x32_bf16 v[114:117], v[160:163], v[214:217], v[114:117]
	v_mfma_f32_16x16x32_bf16 v[110:113], v[152:155], v[236:239], v[110:113]
	v_mfma_f32_16x16x32_bf16 v[106:109], v[160:163], v[236:239], v[106:109]
	v_mfma_f32_16x16x32_bf16 v[102:105], v[152:155], v[244:247], v[102:105]
	v_mfma_f32_16x16x32_bf16 v[98:101], v[160:163], v[244:247], v[98:101]
	v_mfma_f32_16x16x32_bf16 v[94:97], v[166:169], v[182:185], v[94:97]
	v_mfma_f32_16x16x32_bf16 v[90:93], v[174:177], v[182:185], v[90:93]
	v_mfma_f32_16x16x32_bf16 v[86:89], v[166:169], v[210:213], v[86:89]
	v_mfma_f32_16x16x32_bf16 v[82:85], v[174:177], v[210:213], v[82:85]
	v_mfma_f32_16x16x32_bf16 v[78:81], v[166:169], v[218:221], v[78:81]
	v_mfma_f32_16x16x32_bf16 v[74:77], v[174:177], v[218:221], v[74:77]
	v_mfma_f32_16x16x32_bf16 v[70:73], v[166:169], v[240:243], v[70:73]
	v_mfma_f32_16x16x32_bf16 v[66:69], v[174:177], v[240:243], v[66:69]
	v_mfma_f32_16x16x32_bf16 v[94:97], v[170:173], v[206:209], v[94:97]
	v_mfma_f32_16x16x32_bf16 v[90:93], v[178:181], v[206:209], v[90:93]
	v_mfma_f32_16x16x32_bf16 v[86:89], v[170:173], v[214:217], v[86:89]
	v_mfma_f32_16x16x32_bf16 v[82:85], v[178:181], v[214:217], v[82:85]
	v_mfma_f32_16x16x32_bf16 v[78:81], v[170:173], v[236:239], v[78:81]
	v_mfma_f32_16x16x32_bf16 v[74:77], v[178:181], v[236:239], v[74:77]
	v_mfma_f32_16x16x32_bf16 v[70:73], v[170:173], v[244:247], v[70:73]
	v_mfma_f32_16x16x32_bf16 v[66:69], v[178:181], v[244:247], v[66:69]
	s_barrier
	s_add_i32 s9, s9, s0
	s_mov_b32 m0, s9
	ds_read_b128 v[182:185], v165 offset:49152
	ds_read_b128 v[206:209], v165 offset:50176
	ds_read_b128 v[210:213], v165 offset:51200
	ds_read_b128 v[214:217], v165 offset:52224
	ds_read_b128 v[218:221], v165 offset:53248
	ds_read_b128 v[236:239], v165 offset:54272
	ds_read_b128 v[240:243], v165 offset:55296
	ds_read_b128 v[244:247], v165 offset:56320
	s_add_u32 s100, s80, s60
	s_addc_u32 s101, s81, s61
	global_load_lds_dwordx4 v132, s[100:101]
	s_add_i32 m0, s9, 0x2000
	s_add_u32 s10, s80, 0x20080
	s_addc_u32 s11, s81, 0
	s_add_i32 s9, s12, s0
	global_load_lds_dwordx4 v136, s[100:101]
	s_mov_b32 m0, s9
	s_nop 0
	global_load_lds_dwordx4 v132, s[10:11]
	s_add_i32 m0, s9, 0x2000
	s_nop 0
	global_load_lds_dwordx4 v136, s[10:11]
	s_mov_b32 m0, s66
	s_add_u32 s100, s84, s60
	s_addc_u32 s101, s85, s61
	global_load_lds_dwordx4 v130, s[100:101]
	s_mov_b32 m0, s67
	s_nop 0
	global_load_lds_dwordx4 v134, s[100:101]
	s_waitcnt vmcnt(8)
	s_waitcnt lgkmcnt(0)
	s_barrier
	v_mfma_f32_16x16x32_bf16 v[62:65], v[148:151], v[182:185], v[62:65]
	v_mfma_f32_16x16x32_bf16 v[58:61], v[156:159], v[182:185], v[58:61]
	v_mfma_f32_16x16x32_bf16 v[54:57], v[148:151], v[210:213], v[54:57]
	v_mfma_f32_16x16x32_bf16 v[50:53], v[156:159], v[210:213], v[50:53]
	v_mfma_f32_16x16x32_bf16 v[46:49], v[148:151], v[218:221], v[46:49]
	v_mfma_f32_16x16x32_bf16 v[42:45], v[156:159], v[218:221], v[42:45]
	v_mfma_f32_16x16x32_bf16 v[38:41], v[148:151], v[240:243], v[38:41]
	v_mfma_f32_16x16x32_bf16 v[34:37], v[156:159], v[240:243], v[34:37]
	v_mfma_f32_16x16x32_bf16 v[62:65], v[152:155], v[206:209], v[62:65]
	v_mfma_f32_16x16x32_bf16 v[58:61], v[160:163], v[206:209], v[58:61]
	v_mfma_f32_16x16x32_bf16 v[54:57], v[152:155], v[214:217], v[54:57]
	v_mfma_f32_16x16x32_bf16 v[50:53], v[160:163], v[214:217], v[50:53]
	v_mfma_f32_16x16x32_bf16 v[46:49], v[152:155], v[236:239], v[46:49]
	v_mfma_f32_16x16x32_bf16 v[42:45], v[160:163], v[236:239], v[42:45]
	v_mfma_f32_16x16x32_bf16 v[38:41], v[152:155], v[244:247], v[38:41]
	v_mfma_f32_16x16x32_bf16 v[34:37], v[160:163], v[244:247], v[34:37]
	v_mfma_f32_16x16x32_bf16 v[30:33], v[166:169], v[182:185], v[30:33]
	v_mfma_f32_16x16x32_bf16 v[26:29], v[174:177], v[182:185], v[26:29]
	v_mfma_f32_16x16x32_bf16 v[22:25], v[166:169], v[210:213], v[22:25]
	v_mfma_f32_16x16x32_bf16 v[18:21], v[174:177], v[210:213], v[18:21]
	v_mfma_f32_16x16x32_bf16 v[14:17], v[166:169], v[218:221], v[14:17]
	v_mfma_f32_16x16x32_bf16 v[10:13], v[174:177], v[218:221], v[10:13]
	v_mfma_f32_16x16x32_bf16 v[6:9], v[166:169], v[240:243], v[6:9]
	v_mfma_f32_16x16x32_bf16 v[2:5], v[174:177], v[240:243], v[2:5]
	v_mfma_f32_16x16x32_bf16 v[30:33], v[170:173], v[206:209], v[30:33]
	v_mfma_f32_16x16x32_bf16 v[26:29], v[178:181], v[206:209], v[26:29]
	v_mfma_f32_16x16x32_bf16 v[22:25], v[170:173], v[214:217], v[22:25]
	v_mfma_f32_16x16x32_bf16 v[18:21], v[178:181], v[214:217], v[18:21]
	v_mfma_f32_16x16x32_bf16 v[14:17], v[170:173], v[236:239], v[14:17]
	v_mfma_f32_16x16x32_bf16 v[10:13], v[178:181], v[236:239], v[10:13]
	v_mfma_f32_16x16x32_bf16 v[6:9], v[170:173], v[244:247], v[6:9]
	v_mfma_f32_16x16x32_bf16 v[2:5], v[178:181], v[244:247], v[2:5]
	s_barrier
	s_add_i32 s8, s8, 2
	s_add_u32 s46, s46, 0x100
	s_addc_u32 s47, s47, 0
	s_cmp_gt_u32 s8, 29
	s_cbranch_scc0 .LBB0_170
	s_and_b64 vcc, exec, s[54:55]
	s_cbranch_vccz .LBB0_173
	s_barrier

; #define PG8_STAGE(bufoff, gbase, voff) do { _Pragma("unroll") for (int _i = 0; _i < 2; ++_i) \
;         __builtin_amdgcn_global_load_lds((const unsigned*)((const char*)(gbase) + (voff)[_i]), (PG8_LAS unsigned*)(lds + (bufoff) + ldsw + _i * 8192), 16, 0, 0); } while (0)
; #define PG8_LDA(dst, b, h) do { _Pragma("unroll") for (int m = 0; m < 4; ++m) _Pragma("unroll") for (int k = 0; k < 2; ++k) dst[m][k] = *(const PG8_LAS bf16x8*)(lds + PG8_SA(b, h) + aoff + m * 2048 + k * 1024); } while (0)
; #define PG8_LDB(dst, b, h) do { _Pragma("unroll") for (int n = 0; n < 2; ++n) _Pragma("unroll") for (int k = 0; k < 2; ++k) dst[n][k] = *(const PG8_LAS bf16x8*)(lds + PG8_SB(b, h) + boff + n * 2048 + k * 1024); } while (0)
; #define PG8_MMA(ai, bj, At, Bt) do { __builtin_amdgcn_s_setprio(1); _Pragma("unroll") for (int m = 0; m < 4; ++m) _Pragma("unroll") for (int n = 0; n < 2; ++n) _Pragma("unroll") for (int k = 0; k < 2; ++k) \
;         acc[ai][bj][m][n] = __builtin_amdgcn_mfma_f32_16x16x32_bf16(Bt[n][k], At[m][k], acc[ai][bj][m][n], 0, 0, 0); __builtin_amdgcn_s_setprio(0); } while (0)
; #define PG8_WAIT_V(n) asm volatile("s_waitcnt vmcnt(" #n ")" ::: "memory")
; #define PG8_WAIT_L(n) asm volatile("s_waitcnt lgkmcnt(" #n ")" ::: "memory")
; template <class Epi, class Sched, bool ALIGN_EPI = false, bool SP2 = false>
; __device__ __forceinline__ void gemm_phase(PG8_LAS unsigned char* lds, const Gemm g, const Sched& S, const Epi& E) {
;     ...
;             const bool last = (t == nt - 2);
;             const char* a1 = cA + (size_t)(t + 1) * kstep;
;             const char* a2 = last ? nA : cA + (size_t)(t + 2) * kstep; const char* b2 = last ? nB : cB + (size_t)(t + 2) * kstep;
;             const char* a3 = a2 + kstep; const char* b3 = b2 + kstep;
;             if (last && has_next) S.a_ready(nxt);
;             if constexpr (SP2) {
;             PG8_LDB(B0, 0, 0); PG8_LDB(B1, 0, 1); PG8_SCHED; PG8_LDA(At, 0, 0); PG8_STAGE(PG8_SA(1, 1), a1 + hstep, voffA);
;             PG8_WAIT_V(8); PG8_WAIT_L(0); PG8_BAR; PG8_MMA(0, 0, At, B0); PG8_MMA(0, 1, At, B1); PG8_BAR; PG8_SCHED;
;             PG8_LDA(At, 0, 1); PG8_STAGE(PG8_SB(0, 0), b2, voffB); PG8_STAGE(PG8_SB(0, 1), b2 + hstepB, voffB); PG8_STAGE(PG8_SA(0, 0), a2, voffA);
;             PG8_WAIT_V(8); PG8_WAIT_L(0); PG8_BAR; PG8_MMA(1, 0, At, B0); PG8_MMA(1, 1, At, B1); PG8_BAR; PG8_SCHED;
.LBB0_1233:
	s_add_u32 s9, s68, s80
	s_addc_u32 s10, s69, s81
	s_add_u32 s9, s9, 0x100
	s_addc_u32 s10, s10, 0
	s_add_u32 s100, s9, 0x7ff80
	s_addc_u32 s101, s10, 0
	s_add_u32 s11, s36, s80
	s_addc_u32 s12, s37, s81
	s_add_i32 s13, 0, 0x10000
	s_cmpk_eq_i32 s80, 0xf00
	s_cselect_b32 s93, s4, s10
	s_cselect_b32 s92, s5, s9
	v_add_u32_e32 v144, s13, v145
	s_cselect_b32 s85, s6, s12
	s_cselect_b32 s84, s7, s11
	s_add_i32 s9, 0, 0x14000
	ds_read_b128 v[152:155], v144
	ds_read_b128 v[156:159], v144 offset:1024
	ds_read_b128 v[160:163], v144 offset:2048
	ds_read_b128 v[164:167], v144 offset:3072
	v_add_u32_e32 v144, s9, v145
	ds_read_b128 v[168:171], v144
	ds_read_b128 v[172:175], v144 offset:1024
	ds_read_b128 v[176:179], v144 offset:2048
	ds_read_b128 v[180:183], v144 offset:3072
	s_add_i32 m0, s51, 0xc000
	ds_read_b128 v[206:209], v151
	ds_read_b128 v[210:213], v151 offset:1024
	ds_read_b128 v[214:217], v151 offset:2048
	ds_read_b128 v[218:221], v151 offset:3072
	ds_read_b128 v[236:239], v151 offset:4096
	ds_read_b128 v[240:243], v151 offset:5120
	ds_read_b128 v[244:247], v151 offset:6144
	ds_read_b128 v[194:197], v151 offset:7168
	global_load_lds_dwordx4 v136, s[100:101]
	s_add_i32 m0, s51, 0xe000
	s_nop 0
	global_load_lds_dwordx4 v138, s[100:101]
	s_waitcnt vmcnt(8)
	s_waitcnt lgkmcnt(0)
	s_barrier
	v_mfma_f32_16x16x32_bf16 v[126:129], v[152:155], v[206:209], v[126:129]
	v_mfma_f32_16x16x32_bf16 v[122:125], v[160:163], v[206:209], v[122:125]
	v_mfma_f32_16x16x32_bf16 v[118:121], v[152:155], v[214:217], v[118:121]
	v_mfma_f32_16x16x32_bf16 v[114:117], v[160:163], v[214:217], v[114:117]
	v_mfma_f32_16x16x32_bf16 v[110:113], v[152:155], v[236:239], v[110:113]
	v_mfma_f32_16x16x32_bf16 v[106:109], v[160:163], v[236:239], v[106:109]
	v_mfma_f32_16x16x32_bf16 v[102:105], v[152:155], v[244:247], v[102:105]
	v_mfma_f32_16x16x32_bf16 v[98:101], v[160:163], v[244:247], v[98:101]
	v_mfma_f32_16x16x32_bf16 v[126:129], v[156:159], v[210:213], v[126:129]
	v_mfma_f32_16x16x32_bf16 v[122:125], v[164:167], v[210:213], v[122:125]
	v_mfma_f32_16x16x32_bf16 v[118:121], v[156:159], v[218:221], v[118:121]
	v_mfma_f32_16x16x32_bf16 v[114:117], v[164:167], v[218:221], v[114:117]
	v_mfma_f32_16x16x32_bf16 v[110:113], v[156:159], v[240:243], v[110:113]
	v_mfma_f32_16x16x32_bf16 v[106:109], v[164:167], v[240:243], v[106:109]
	v_mfma_f32_16x16x32_bf16 v[102:105], v[156:159], v[194:197], v[102:105]
	v_mfma_f32_16x16x32_bf16 v[98:101], v[164:167], v[194:197], v[98:101]
	v_mfma_f32_16x16x32_bf16 v[94:97], v[168:171], v[206:209], v[94:97]
	v_mfma_f32_16x16x32_bf16 v[90:93], v[176:179], v[206:209], v[90:93]
	v_mfma_f32_16x16x32_bf16 v[86:89], v[168:171], v[214:217], v[86:89]
	v_mfma_f32_16x16x32_bf16 v[82:85], v[176:179], v[214:217], v[82:85]
	v_mfma_f32_16x16x32_bf16 v[78:81], v[168:171], v[236:239], v[78:81]
	v_mfma_f32_16x16x32_bf16 v[74:77], v[176:179], v[236:239], v[74:77]
	v_mfma_f32_16x16x32_bf16 v[70:73], v[168:171], v[244:247], v[70:73]
	v_mfma_f32_16x16x32_bf16 v[66:69], v[176:179], v[244:247], v[66:69]
	v_mfma_f32_16x16x32_bf16 v[94:97], v[172:175], v[210:213], v[94:97]
	v_mfma_f32_16x16x32_bf16 v[90:93], v[180:183], v[210:213], v[90:93]
	v_mfma_f32_16x16x32_bf16 v[86:89], v[172:175], v[218:221], v[86:89]
	v_mfma_f32_16x16x32_bf16 v[82:85], v[180:183], v[218:221], v[82:85]
	v_mfma_f32_16x16x32_bf16 v[78:81], v[172:175], v[240:243], v[78:81]
	v_mfma_f32_16x16x32_bf16 v[74:77], v[180:183], v[240:243], v[74:77]
	v_mfma_f32_16x16x32_bf16 v[70:73], v[172:175], v[194:197], v[70:73]
	v_mfma_f32_16x16x32_bf16 v[66:69], v[180:183], v[194:197], v[66:69]
	s_barrier
	s_add_i32 s10, s13, s42
	s_mov_b32 m0, s10
	ds_read_b128 v[194:197], v151 offset:16384
	ds_read_b128 v[206:209], v151 offset:17408
	ds_read_b128 v[210:213], v151 offset:18432
	ds_read_b128 v[214:217], v151 offset:19456
	ds_read_b128 v[218:221], v151 offset:20480
	ds_read_b128 v[236:239], v151 offset:21504
	ds_read_b128 v[240:243], v151 offset:22528
	ds_read_b128 v[244:247], v151 offset:23552
	global_load_lds_dwordx4 v130, s[84:85]
	s_add_i32 m0, s10, 0x2000
	s_add_u32 s10, s84, 0x20000
	s_addc_u32 s11, s85, 0
	s_add_i32 s9, s9, s42
	global_load_lds_dwordx4 v134, s[84:85]
	s_mov_b32 m0, s9
	s_nop 0
	global_load_lds_dwordx4 v130, s[10:11]
	s_add_i32 m0, s9, 0x2000
	s_nop 0
	global_load_lds_dwordx4 v134, s[10:11]
	s_mov_b32 m0, s51
	s_nop 0
	global_load_lds_dwordx4 v190, s[92:93]
	s_mov_b32 m0, s67
	s_nop 0
	global_load_lds_dwordx4 v132, s[92:93]
	s_waitcnt vmcnt(8)
	s_waitcnt lgkmcnt(0)
	s_barrier
	v_mfma_f32_16x16x32_bf16 v[62:65], v[152:155], v[194:197], v[62:65]
	v_mfma_f32_16x16x32_bf16 v[58:61], v[160:163], v[194:197], v[58:61]
	v_mfma_f32_16x16x32_bf16 v[54:57], v[152:155], v[210:213], v[54:57]
	v_mfma_f32_16x16x32_bf16 v[50:53], v[160:163], v[210:213], v[50:53]
	v_mfma_f32_16x16x32_bf16 v[46:49], v[152:155], v[218:221], v[46:49]
	v_mfma_f32_16x16x32_bf16 v[42:45], v[160:163], v[218:221], v[42:45]
	v_mfma_f32_16x16x32_bf16 v[38:41], v[152:155], v[240:243], v[38:41]
	v_mfma_f32_16x16x32_bf16 v[34:37], v[160:163], v[240:243], v[34:37]
	v_mfma_f32_16x16x32_bf16 v[62:65], v[156:159], v[206:209], v[62:65]
	v_mfma_f32_16x16x32_bf16 v[58:61], v[164:167], v[206:209], v[58:61]
	v_mfma_f32_16x16x32_bf16 v[54:57], v[156:159], v[214:217], v[54:57]
	v_mfma_f32_16x16x32_bf16 v[50:53], v[164:167], v[214:217], v[50:53]
	v_mfma_f32_16x16x32_bf16 v[46:49], v[156:159], v[236:239], v[46:49]
	v_mfma_f32_16x16x32_bf16 v[42:45], v[164:167], v[236:239], v[42:45]
	v_mfma_f32_16x16x32_bf16 v[38:41], v[156:159], v[244:247], v[38:41]
	v_mfma_f32_16x16x32_bf16 v[34:37], v[164:167], v[244:247], v[34:37]
	v_mfma_f32_16x16x32_bf16 v[30:33], v[168:171], v[194:197], v[30:33]
	v_mfma_f32_16x16x32_bf16 v[26:29], v[176:179], v[194:197], v[26:29]
	v_mfma_f32_16x16x32_bf16 v[22:25], v[168:171], v[210:213], v[22:25]
	v_mfma_f32_16x16x32_bf16 v[18:21], v[176:179], v[210:213], v[18:21]
	v_mfma_f32_16x16x32_bf16 v[14:17], v[168:171], v[218:221], v[14:17]
	v_mfma_f32_16x16x32_bf16 v[10:13], v[176:179], v[218:221], v[10:13]
	v_mfma_f32_16x16x32_bf16 v[6:9], v[168:171], v[240:243], v[6:9]
	v_mfma_f32_16x16x32_bf16 v[2:5], v[176:179], v[240:243], v[2:5]
	v_mfma_f32_16x16x32_bf16 v[30:33], v[172:175], v[206:209], v[30:33]
	v_mfma_f32_16x16x32_bf16 v[26:29], v[180:183], v[206:209], v[26:29]
	v_mfma_f32_16x16x32_bf16 v[22:25], v[172:175], v[214:217], v[22:25]
	v_mfma_f32_16x16x32_bf16 v[18:21], v[180:183], v[214:217], v[18:21]
	v_mfma_f32_16x16x32_bf16 v[14:17], v[172:175], v[236:239], v[14:17]
	v_mfma_f32_16x16x32_bf16 v[10:13], v[180:183], v[236:239], v[10:13]
	v_mfma_f32_16x16x32_bf16 v[6:9], v[172:175], v[244:247], v[6:9]
	v_mfma_f32_16x16x32_bf16 v[2:5], v[180:183], v[244:247], v[2:5]
	s_barrier
; #define PG8_STAGE(bufoff, gbase, voff) do { _Pragma("unroll") for (int _i = 0; _i < 2; ++_i) \
;         __builtin_amdgcn_global_load_lds((const unsigned*)((const char*)(gbase) + (voff)[_i]), (PG8_LAS unsigned*)(lds + (bufoff) + ldsw + _i * 8192), 16, 0, 0); } while (0)
; #define PG8_LDA(dst, b, h) do { _Pragma("unroll") for (int m = 0; m < 4; ++m) _Pragma("unroll") for (int k = 0; k < 2; ++k) dst[m][k] = *(const PG8_LAS bf16x8*)(lds + PG8_SA(b, h) + aoff + m * 2048 + k * 1024); } while (0)
; #define PG8_LDB(dst, b, h) do { _Pragma("unroll") for (int n = 0; n < 2; ++n) _Pragma("unroll") for (int k = 0; k < 2; ++k) dst[n][k] = *(const PG8_LAS bf16x8*)(lds + PG8_SB(b, h) + boff + n * 2048 + k * 1024); } while (0)
; #define PG8_MMA(ai, bj, At, Bt) do { __builtin_amdgcn_s_setprio(1); _Pragma("unroll") for (int m = 0; m < 4; ++m) _Pragma("unroll") for (int n = 0; n < 2; ++n) _Pragma("unroll") for (int k = 0; k < 2; ++k) \
;         acc[ai][bj][m][n] = __builtin_amdgcn_mfma_f32_16x16x32_bf16(Bt[n][k], At[m][k], acc[ai][bj][m][n], 0, 0, 0); __builtin_amdgcn_s_setprio(0); } while (0)
; #define PG8_WAIT_V(n) asm volatile("s_waitcnt vmcnt(" #n ")" ::: "memory")
; #define PG8_WAIT_L(n) asm volatile("s_waitcnt lgkmcnt(" #n ")" ::: "memory")
; #define PG8_BAR __builtin_amdgcn_s_barrier()
; #define PG8_SCHED __builtin_amdgcn_sched_barrier(0)
; template <class Epi, class Sched, bool ALIGN_EPI = false, bool SP2 = false>
; __device__ __forceinline__ void gemm_phase(PG8_LAS unsigned char* lds, const Gemm g, const Sched& S, const Epi& E) {
;     ...
;             PG8_LDB(B0, 1, 0); PG8_LDB(B1, 1, 1); PG8_SCHED; PG8_LDA(At, 1, 0); PG8_STAGE(PG8_SA(0, 1), a2 + hstep, voffA);
;             PG8_WAIT_V(8); PG8_WAIT_L(0); PG8_BAR; PG8_MMA(0, 0, At, B0); PG8_MMA(0, 1, At, B1); PG8_BAR; PG8_SCHED;
;             PG8_LDA(At, 1, 1); PG8_STAGE(PG8_SB(1, 0), b3, voffB); PG8_STAGE(PG8_SB(1, 1), b3 + hstepB, voffB); PG8_STAGE(PG8_SA(1, 0), a3, voffA);
;             PG8_WAIT_V(8); PG8_WAIT_L(0); PG8_BAR; PG8_MMA(1, 0, At, B0); PG8_MMA(1, 1, At, B1); PG8_BAR; PG8_SCHED;
	s_add_i32 s9, 0, 0x18000
	v_add_u32_e32 v144, s9, v145
	s_add_i32 s12, 0, 0x1c000
	ds_read_b128 v[152:155], v144
	ds_read_b128 v[156:159], v144 offset:1024
	ds_read_b128 v[160:163], v144 offset:2048
	ds_read_b128 v[164:167], v144 offset:3072
	v_add_u32_e32 v144, s12, v145
	ds_read_b128 v[168:171], v144
	ds_read_b128 v[172:175], v144 offset:1024
	ds_read_b128 v[176:179], v144 offset:2048
	ds_read_b128 v[180:183], v144 offset:3072
	s_add_u32 s10, s92, 0x80000
	s_addc_u32 s11, s93, 0
	s_mov_b32 m0, s74
	ds_read_b128 v[194:197], v151 offset:32768
	ds_read_b128 v[206:209], v151 offset:33792
	ds_read_b128 v[210:213], v151 offset:34816
	ds_read_b128 v[214:217], v151 offset:35840
	ds_read_b128 v[218:221], v151 offset:36864
	ds_read_b128 v[236:239], v151 offset:37888
	ds_read_b128 v[240:243], v151 offset:38912
	ds_read_b128 v[244:247], v151 offset:39936
	global_load_lds_dwordx4 v190, s[10:11]
	s_mov_b32 m0, s75
	s_nop 0
	global_load_lds_dwordx4 v132, s[10:11]
	s_waitcnt vmcnt(8)
	s_waitcnt lgkmcnt(0)
	s_barrier
	v_mfma_f32_16x16x32_bf16 v[126:129], v[152:155], v[194:197], v[126:129]
	v_mfma_f32_16x16x32_bf16 v[122:125], v[160:163], v[194:197], v[122:125]
	v_mfma_f32_16x16x32_bf16 v[118:121], v[152:155], v[210:213], v[118:121]
	v_mfma_f32_16x16x32_bf16 v[114:117], v[160:163], v[210:213], v[114:117]
	v_mfma_f32_16x16x32_bf16 v[110:113], v[152:155], v[218:221], v[110:113]
	v_mfma_f32_16x16x32_bf16 v[106:109], v[160:163], v[218:221], v[106:109]
	v_mfma_f32_16x16x32_bf16 v[102:105], v[152:155], v[240:243], v[102:105]
	v_mfma_f32_16x16x32_bf16 v[98:101], v[160:163], v[240:243], v[98:101]
	v_mfma_f32_16x16x32_bf16 v[126:129], v[156:159], v[206:209], v[126:129]
	v_mfma_f32_16x16x32_bf16 v[122:125], v[164:167], v[206:209], v[122:125]
	v_mfma_f32_16x16x32_bf16 v[118:121], v[156:159], v[214:217], v[118:121]
	v_mfma_f32_16x16x32_bf16 v[114:117], v[164:167], v[214:217], v[114:117]
	v_mfma_f32_16x16x32_bf16 v[110:113], v[156:159], v[236:239], v[110:113]
	v_mfma_f32_16x16x32_bf16 v[106:109], v[164:167], v[236:239], v[106:109]
	v_mfma_f32_16x16x32_bf16 v[102:105], v[156:159], v[244:247], v[102:105]
	v_mfma_f32_16x16x32_bf16 v[98:101], v[164:167], v[244:247], v[98:101]
	v_mfma_f32_16x16x32_bf16 v[94:97], v[168:171], v[194:197], v[94:97]
	v_mfma_f32_16x16x32_bf16 v[90:93], v[176:179], v[194:197], v[90:93]
	v_mfma_f32_16x16x32_bf16 v[86:89], v[168:171], v[210:213], v[86:89]
	v_mfma_f32_16x16x32_bf16 v[82:85], v[176:179], v[210:213], v[82:85]
	v_mfma_f32_16x16x32_bf16 v[78:81], v[168:171], v[218:221], v[78:81]
	v_mfma_f32_16x16x32_bf16 v[74:77], v[176:179], v[218:221], v[74:77]
	v_mfma_f32_16x16x32_bf16 v[70:73], v[168:171], v[240:243], v[70:73]
	v_mfma_f32_16x16x32_bf16 v[66:69], v[176:179], v[240:243], v[66:69]
	v_mfma_f32_16x16x32_bf16 v[94:97], v[172:175], v[206:209], v[94:97]
	v_mfma_f32_16x16x32_bf16 v[90:93], v[180:183], v[206:209], v[90:93]
	v_mfma_f32_16x16x32_bf16 v[86:89], v[172:175], v[214:217], v[86:89]
	v_mfma_f32_16x16x32_bf16 v[82:85], v[180:183], v[214:217], v[82:85]
	v_mfma_f32_16x16x32_bf16 v[78:81], v[172:175], v[236:239], v[78:81]
	v_mfma_f32_16x16x32_bf16 v[74:77], v[180:183], v[236:239], v[74:77]
	v_mfma_f32_16x16x32_bf16 v[70:73], v[172:175], v[244:247], v[70:73]
	v_mfma_f32_16x16x32_bf16 v[66:69], v[180:183], v[244:247], v[66:69]
	s_barrier
	s_add_i32 s9, s9, s42
	s_mov_b32 m0, s9
	ds_read_b128 v[194:197], v151 offset:49152
	ds_read_b128 v[206:209], v151 offset:50176
	ds_read_b128 v[210:213], v151 offset:51200
	ds_read_b128 v[214:217], v151 offset:52224
	ds_read_b128 v[218:221], v151 offset:53248
	ds_read_b128 v[236:239], v151 offset:54272
	ds_read_b128 v[240:243], v151 offset:55296
	ds_read_b128 v[244:247], v151 offset:56320
	s_add_u32 s100, s84, s60
	s_addc_u32 s101, s85, s61
	global_load_lds_dwordx4 v130, s[100:101]
	s_add_i32 m0, s9, 0x2000
	s_add_u32 s10, s84, 0x20080
	s_addc_u32 s11, s85, 0
	s_add_i32 s9, s12, s42
	global_load_lds_dwordx4 v134, s[100:101]
	s_mov_b32 m0, s9
	s_nop 0
	global_load_lds_dwordx4 v130, s[10:11]
	s_add_i32 m0, s9, 0x2000
	s_nop 0
	global_load_lds_dwordx4 v134, s[10:11]
	s_mov_b32 m0, s82
	s_add_u32 s100, s92, s60
	s_addc_u32 s101, s93, s61
	global_load_lds_dwordx4 v190, s[100:101]
	s_mov_b32 m0, s86
	s_nop 0
	global_load_lds_dwordx4 v132, s[100:101]
	s_waitcnt vmcnt(8)
	s_waitcnt lgkmcnt(0)
	s_barrier
	v_mfma_f32_16x16x32_bf16 v[62:65], v[152:155], v[194:197], v[62:65]
	v_mfma_f32_16x16x32_bf16 v[58:61], v[160:163], v[194:197], v[58:61]
	v_mfma_f32_16x16x32_bf16 v[54:57], v[152:155], v[210:213], v[54:57]
	v_mfma_f32_16x16x32_bf16 v[50:53], v[160:163], v[210:213], v[50:53]
	v_mfma_f32_16x16x32_bf16 v[46:49], v[152:155], v[218:221], v[46:49]
	v_mfma_f32_16x16x32_bf16 v[42:45], v[160:163], v[218:221], v[42:45]
	v_mfma_f32_16x16x32_bf16 v[38:41], v[152:155], v[240:243], v[38:41]
	v_mfma_f32_16x16x32_bf16 v[34:37], v[160:163], v[240:243], v[34:37]
	v_mfma_f32_16x16x32_bf16 v[62:65], v[156:159], v[206:209], v[62:65]
	v_mfma_f32_16x16x32_bf16 v[58:61], v[164:167], v[206:209], v[58:61]
	v_mfma_f32_16x16x32_bf16 v[54:57], v[156:159], v[214:217], v[54:57]
	v_mfma_f32_16x16x32_bf16 v[50:53], v[164:167], v[214:217], v[50:53]
	v_mfma_f32_16x16x32_bf16 v[46:49], v[156:159], v[236:239], v[46:49]
	v_mfma_f32_16x16x32_bf16 v[42:45], v[164:167], v[236:239], v[42:45]
	v_mfma_f32_16x16x32_bf16 v[38:41], v[156:159], v[244:247], v[38:41]
	v_mfma_f32_16x16x32_bf16 v[34:37], v[164:167], v[244:247], v[34:37]
	v_mfma_f32_16x16x32_bf16 v[30:33], v[168:171], v[194:197], v[30:33]
	v_mfma_f32_16x16x32_bf16 v[26:29], v[176:179], v[194:197], v[26:29]
	v_mfma_f32_16x16x32_bf16 v[22:25], v[168:171], v[210:213], v[22:25]
	v_mfma_f32_16x16x32_bf16 v[18:21], v[176:179], v[210:213], v[18:21]
	v_mfma_f32_16x16x32_bf16 v[14:17], v[168:171], v[218:221], v[14:17]
	v_mfma_f32_16x16x32_bf16 v[10:13], v[176:179], v[218:221], v[10:13]
	v_mfma_f32_16x16x32_bf16 v[6:9], v[168:171], v[240:243], v[6:9]
	v_mfma_f32_16x16x32_bf16 v[2:5], v[176:179], v[240:243], v[2:5]
	v_mfma_f32_16x16x32_bf16 v[30:33], v[172:175], v[206:209], v[30:33]
	v_mfma_f32_16x16x32_bf16 v[26:29], v[180:183], v[206:209], v[26:29]
	v_mfma_f32_16x16x32_bf16 v[22:25], v[172:175], v[214:217], v[22:25]
	v_mfma_f32_16x16x32_bf16 v[18:21], v[180:183], v[214:217], v[18:21]
	v_mfma_f32_16x16x32_bf16 v[14:17], v[172:175], v[236:239], v[14:17]
	v_mfma_f32_16x16x32_bf16 v[10:13], v[180:183], v[236:239], v[10:13]
	v_mfma_f32_16x16x32_bf16 v[6:9], v[172:175], v[244:247], v[6:9]
	v_mfma_f32_16x16x32_bf16 v[2:5], v[180:183], v[244:247], v[2:5]
	s_barrier
	s_add_i32 s8, s8, 2
	s_add_u32 s80, s80, 0x100
	s_addc_u32 s81, s81, 0
	s_cmp_gt_u32 s8, 29
	s_cbranch_scc0 .LBB0_1233
	s_and_b64 vcc, exec, s[62:63]
	s_cbranch_vccz .LBB0_1236
	s_barrier
